# v92 + phase 0 row loop: scalar-load L2 prefetch of the row two iterations ahead
# baseline (speedup 1.0000x reference)
.LBB0_808:
	s_or_b64 exec, exec, s[36:37]
	v_readfirstlane_b32 s2, v20
	v_readlane_b32 s22, v212, 36
	s_lshl_b32 s22, s22, 1
	s_add_i32 s2, s2, s22
	s_cmp_gt_i32 s2, s43
	s_cbranch_scc1 .Lp0_nopf
	s_lshl_b32 s2, s22, 12
	v_readfirstlane_b32 s22, v22
	v_readfirstlane_b32 s23, v23
	s_nop 0
	s_add_u32 s22, s22, s2
	s_addc_u32 s23, s23, 0
	s_load_dword s100, s[22:23], 0x0
	s_load_dword s100, s[22:23], 0x80
	s_load_dword s100, s[22:23], 0x100
	s_load_dword s100, s[22:23], 0x180
	s_load_dword s100, s[22:23], 0x200
	s_load_dword s100, s[22:23], 0x280
	s_load_dword s100, s[22:23], 0x300
	s_load_dword s100, s[22:23], 0x380
	s_load_dword s100, s[22:23], 0x400
	s_load_dword s100, s[22:23], 0x480
	s_load_dword s100, s[22:23], 0x500
	s_load_dword s100, s[22:23], 0x580
	s_load_dword s100, s[22:23], 0x600
	s_load_dword s100, s[22:23], 0x680
	s_load_dword s100, s[22:23], 0x700
	s_load_dword s100, s[22:23], 0x780
	s_load_dword s100, s[22:23], 0x800
	s_load_dword s100, s[22:23], 0x880
	s_load_dword s100, s[22:23], 0x900
	s_load_dword s100, s[22:23], 0x980
	s_load_dword s100, s[22:23], 0xa00
	s_load_dword s100, s[22:23], 0xa80
	s_load_dword s100, s[22:23], 0xb00
	s_load_dword s100, s[22:23], 0xb80
	s_load_dword s100, s[22:23], 0xc00
	s_load_dword s100, s[22:23], 0xc80
	s_load_dword s100, s[22:23], 0xd00
	s_load_dword s100, s[22:23], 0xd80
	s_load_dword s100, s[22:23], 0xe00
	s_load_dword s100, s[22:23], 0xe80
	s_load_dword s100, s[22:23], 0xf00
	s_load_dword s100, s[22:23], 0xf80
.Lp0_nopf:
	v_lshlrev_b32_e32 v64, 2, v16
	v_lshl_add_u64 v[0:1], v[0:1], 0, v[64:65]
	global_load_dwordx4 v[12:15], v[0:1], off
	global_load_dwordx4 v[8:11], v[0:1], off offset:1024
	global_load_dwordx4 v[4:7], v[0:1], off offset:2048
	s_nop 0
	global_load_dwordx4 v[0:3], v[0:1], off offset:3072
	v_mov_b32_e32 v25, v65
	s_waitcnt vmcnt(3)
	v_mul_f32_e32 v28, v13, v13
	s_waitcnt vmcnt(2)
	v_mul_f32_e32 v29, v9, v9
	s_waitcnt vmcnt(1)
	v_mul_f32_e32 v30, v5, v5
	v_fmac_f32_e32 v28, v12, v12
	v_fmac_f32_e32 v29, v8, v8
	s_waitcnt vmcnt(0)
	v_mul_f32_e32 v31, v1, v1
	v_fmac_f32_e32 v30, v4, v4
	v_fmac_f32_e32 v28, v14, v14
	v_fmac_f32_e32 v29, v10, v10
	v_fmac_f32_e32 v31, v0, v0
	v_fmac_f32_e32 v30, v6, v6
	v_fmac_f32_e32 v28, v15, v15
	v_fmac_f32_e32 v29, v11, v11
	v_fmac_f32_e32 v31, v2, v2
	v_fmac_f32_e32 v30, v7, v7
	v_add_f32_e32 v28, v28, v29
	v_fmac_f32_e32 v31, v3, v3
	v_add_f32_e32 v28, v28, v30
	v_add_f32_e32 v28, v28, v31
	s_nop 1
	v_add_f32_dpp v28, v28, v28 quad_perm:[1,0,3,2] row_mask:0xf bank_mask:0xf bound_ctrl:1
	s_nop 1
	v_add_f32_dpp v28, v28, v28 quad_perm:[2,3,0,1] row_mask:0xf bank_mask:0xf bound_ctrl:1
	s_nop 1
	v_add_f32_dpp v28, v28, v28 row_half_mirror row_mask:0xf bank_mask:0xf bound_ctrl:1
	s_nop 1
	v_add_f32_dpp v28, v28, v28 row_mirror row_mask:0xf bank_mask:0xf bound_ctrl:1
	s_nop 1
	v_mov_b32_dpp v25, v28 row_bcast:15 row_mask:0xa bank_mask:0xf
	v_add_f32_e32 v25, v28, v25
	v_mov_b32_e32 v28, v65
	s_nop 1
	v_mov_b32_dpp v28, v25 row_bcast:31 row_mask:0xc bank_mask:0xf
	v_add_f32_e32 v25, v25, v28
	s_nop 0
	v_readlane_b32 s2, v25, 63
	s_and_saveexec_b64 s[36:37], s[0:1]
	s_cbranch_execz .LBB0_810
	v_readlane_b32 s22, v215, 54
	v_readlane_b32 s23, v215, 55
	v_mov_b32_e32 v25, s2
	s_nop 0
	v_lshl_add_u64 v[28:29], v[26:27], 2, s[22:23]
	global_store_dword v[28:29], v25, off

	.amdhsa_kernel _Z4mega6Params
		.amdhsa_group_segment_fixed_size 0
		.amdhsa_private_segment_fixed_size 0
		.amdhsa_kernarg_size 488
		.amdhsa_user_sgpr_count 2
		.amdhsa_user_sgpr_dispatch_ptr 0
		.amdhsa_user_sgpr_queue_ptr 0
		.amdhsa_user_sgpr_kernarg_segment_ptr 1
		.amdhsa_user_sgpr_dispatch_id 0
		.amdhsa_user_sgpr_kernarg_preload_length 0
		.amdhsa_user_sgpr_kernarg_preload_offset 0
		.amdhsa_user_sgpr_private_segment_size 0
		.amdhsa_uses_dynamic_stack 0
		.amdhsa_enable_private_segment 0
		.amdhsa_system_sgpr_workgroup_id_x 1
		.amdhsa_system_sgpr_workgroup_id_y 0
		.amdhsa_system_sgpr_workgroup_id_z 0
		.amdhsa_system_sgpr_workgroup_info 0
		.amdhsa_system_vgpr_workitem_id 2
		.amdhsa_next_free_vgpr 256
		.amdhsa_next_free_sgpr 101
		.amdhsa_accum_offset 220
		.amdhsa_reserve_vcc 1
		.amdhsa_float_round_mode_32 0
		.amdhsa_float_round_mode_16_64 0
		.amdhsa_float_denorm_mode_32 3
		.amdhsa_float_denorm_mode_16_64 3
		.amdhsa_dx10_clamp 1
		.amdhsa_ieee_mode 1
		.amdhsa_fp16_overflow 0
		.amdhsa_tg_split 0
		.amdhsa_exception_fp_ieee_invalid_op 0
		.amdhsa_exception_fp_denorm_src 0
		.amdhsa_exception_fp_ieee_div_zero 0
		.amdhsa_exception_fp_ieee_overflow 0
		.amdhsa_exception_fp_ieee_underflow 0
		.amdhsa_exception_fp_ieee_inexact 0
		.amdhsa_exception_int_div_zero 0
	.end_amdhsa_kernel

amdhsa.kernels:
  - .agpr_count:     36
    .args:
      - .offset:         0
        .size:           232
        .value_kind:     by_value
      - .offset:         232
        .size:           4
        .value_kind:     hidden_block_count_x
      - .offset:         236
        .size:           4
        .value_kind:     hidden_block_count_y
      - .offset:         240
        .size:           4
        .value_kind:     hidden_block_count_z
      - .offset:         244
        .size:           2
        .value_kind:     hidden_group_size_x
      - .offset:         246
        .size:           2
        .value_kind:     hidden_group_size_y
      - .offset:         248
        .size:           2
        .value_kind:     hidden_group_size_z
      - .offset:         250
        .size:           2
        .value_kind:     hidden_remainder_x
      - .offset:         252
        .size:           2
        .value_kind:     hidden_remainder_y
      - .offset:         254
        .size:           2
        .value_kind:     hidden_remainder_z
      - .offset:         272
        .size:           8
        .value_kind:     hidden_global_offset_x
      - .offset:         280
        .size:           8
        .value_kind:     hidden_global_offset_y
      - .offset:         288
        .size:           8
        .value_kind:     hidden_global_offset_z
      - .offset:         296
        .size:           2
        .value_kind:     hidden_grid_dims
      - .offset:         320
        .size:           8
        .value_kind:     hidden_multigrid_sync_arg
      - .offset:         352
        .size:           4
        .value_kind:     hidden_dynamic_lds_size
    .group_segment_fixed_size: 0
    .kernarg_segment_align: 8
    .kernarg_segment_size: 488
    .language:       OpenCL C
    .language_version:
      - 2
      - 0
    .max_flat_workgroup_size: 512
    .name:           _Z4mega6Params
    .private_segment_fixed_size: 0
    .sgpr_count:     107
    .sgpr_spill_count: 308
    .symbol:         _Z4mega6Params.kd
    .uniform_work_group_size: 1
    .uses_dynamic_stack: false
    .vgpr_count:     220
    .vgpr_spill_count: 0
    .wavefront_size: 64
